# windowed attention: K/V tiles fetched by LDS-DMA into a 3-slot linear staging area two tiles ahead (was register-staged one tile ahead), copied LDS-to-LDS into the padded tile image
# baseline (speedup 1.0000x reference)
.LBB0_374:
	v_mov_b32_e32 v8, v247
	s_bfe_u32 s4, s17, 0x10004
	s_lshl_b32 s58, s4, 7
	v_readfirstlane_b32 s5, v8
	s_and_b32 s22, s17, 15
	s_lshl_b32 s4, s4, 2
	s_ashr_i32 s6, s5, 7
	s_add_i32 s4, s6, s4
	s_and_b32 s5, s5, 64
	s_lshl_b32 s6, s22, 7
	v_and_b32_e32 v9, 31, v8
	s_or_b32 s6, s5, s6
	s_ashr_i32 s10, s17, 5
	v_or_b32_e32 v0, s6, v9
	s_lshl_b32 s6, s4, 6
	s_ashr_i32 s11, s10, 31
	s_ashr_i32 s7, s6, 31
	s_and_b32 s25, s16, 15
	s_lshl_b64 s[14:15], s[10:11], 11
	s_lshl_b64 s[6:7], s[6:7], 1
	v_bfe_u32 v10, v8, 5, 1
	s_add_u32 s20, s8, s6
	v_or_b32_e32 v206, s14, v0
	s_addc_u32 s21, s9, s7
	v_lshlrev_b32_e32 v0, 4, v10
	v_lshl_add_u64 v[2:3], s[20:21], 0, v[0:1]
	v_mad_u64_u32 v[2:3], s[20:21], v206, s91, v[2:3]
	v_mad_i32_i24 v3, s15, v246, v3
	s_mov_b32 s11, 0x24000
	global_load_dwordx4 v[98:101], v[2:3], off
	global_load_dwordx4 v[102:105], v[2:3], off offset:32
	global_load_dwordx4 v[106:109], v[2:3], off offset:64
	global_load_dwordx4 v[110:113], v[2:3], off offset:96
	v_lshl_add_u64 v[4:5], v[2:3], 0, s[34:35]
	v_add_co_u32_e32 v2, vcc, s11, v2
	v_mov_b64_e32 v[6:7], s[8:9]
	s_nop 0
	v_addc_co_u32_e32 v3, vcc, 0, v3, vcc
	global_load_dwordx4 v[114:117], v[2:3], off
	global_load_dwordx4 v[118:121], v[4:5], off offset:32
	global_load_dwordx4 v[122:125], v[4:5], off offset:64
	global_load_dwordx4 v[126:129], v[4:5], off offset:96
	v_sub_co_u32_e64 v4, s[20:21], s22, 1
	v_ashrrev_i32_e32 v5, 31, v4
	v_ashrrev_i32_e32 v2, 3, v8
	v_lshlrev_b64 v[4:5], 7, v[4:5]
	v_lshl_add_u64 v[4:5], v[4:5], 0, s[14:15]
	v_ashrrev_i32_e32 v3, 31, v2
	v_lshl_add_u64 v[4:5], v[4:5], 0, v[2:3]
	v_mov_b32_e32 v207, s15
	v_mad_u64_u32 v[6:7], s[14:15], v4, s91, v[6:7]
	v_lshlrev_b32_e32 v3, 4, v8
	v_mad_i32_i24 v7, v5, s91, v7
	v_and_b32_e32 v4, 0x70, v3
	v_mov_b32_e32 v5, v1
	s_and_b64 s[14:15], s[20:21], exec
	v_lshl_add_u64 v[6:7], v[6:7], 0, s[58:59]
	v_mad_u64_u32 v[208:209], s[14:15], v2, s33, v[4:5]
	s_cselect_b32 s26, 2, 0
	v_lshl_add_u64 v[6:7], v[6:7], 0, v[4:5]
	s_mul_i32 s14, s26, 0x48000
	s_mov_b32 s15, s59
	v_lshl_add_u64 v[6:7], v[6:7], 0, s[14:15]
	global_load_dwordx4 v[130:133], v[6:7], off offset:1024
	global_load_dwordx4 v[134:137], v[6:7], off offset:1280
	s_cmp_eq_u32 s22, 15
	s_cselect_b32 s20, 4, 6
	s_lshl_b32 s11, s26, 6
	s_mul_i32 s25, s25, 0x90000
	s_or_b32 s21, s5, 0x11f
	s_or_b32 s22, s5, 32
	s_or_b32 s23, s5, 0x13f
	s_or_b32 s24, s11, 63
	s_mul_hi_i32 s11, s10, 0x900000
	s_mul_i32 s10, s10, 0x900000
	s_add_u32 s10, s10, s25
	v_add_u32_e32 v3, 0, v208
	v_mul_lo_u32 v5, v2, 48
	s_addc_u32 s11, s11, 0
	v_mad_u32_u24 v226, v9, s33, v0
	v_lshlrev_b32_e32 v224, 2, v10
	v_lshrrev_b32_e32 v0, 2, v8
	s_add_u32 s10, s10, s14
	v_add_u32_e32 v225, v208, v5
	v_and_or_b32 v0, v0, 3, v224
	s_addc_u32 s11, s11, 0
	v_mul_u32_u24_e32 v0, 0xc0, v0
	v_mov_b64_e32 v[6:7], s[10:11]
	v_mov_b32_e32 v14, v1
	v_mov_b32_e32 v15, v1
	v_mov_b32_e32 v10, v1
	v_mov_b32_e32 v11, v1
	v_mov_b32_e32 v12, v1
	v_mov_b32_e32 v13, v1
	v_mov_b32_e32 v228, 0
	v_mov_b32_e32 v209, 0
	s_waitcnt vmcnt(1)
	ds_write_b128 v3, v[130:133]
	v_add_u32_e32 v3, v3, v5
	s_waitcnt vmcnt(0)
	ds_write_b128 v3, v[134:137] offset:9216
	v_lshlrev_b32_e32 v3, 1, v8
	v_lshlrev_b32_e32 v5, 3, v8
	v_and_b32_e32 v3, 32, v3
	v_and_b32_e32 v5, 24, v5
	v_or3_b32 v0, v3, v5, v0
	v_mad_i64_i32 v[2:3], s[10:11], v2, s91, v[6:7]
	v_add_u32_e32 v227, 0x2400, v0
	v_sub_u32_e32 v0, v224, v9
	v_or3_b32 v2, v2, s58, v4
	v_subrev_u32_e32 v229, s5, v0
	v_lshl_add_u64 v[210:211], s[0:1], 0, v[2:3]
	v_mov_b32_e32 v0, v1
	v_mov_b32_e32 v2, v1
	v_mov_b32_e32 v3, v1
	v_mov_b32_e32 v4, v1
	v_mov_b32_e32 v5, v1
	v_mov_b32_e32 v6, v1
	v_mov_b32_e32 v7, v1
	v_mov_b32_e32 v8, v1
	v_mov_b32_e32 v9, v1
	v_mov_b64_e32 v[64:65], v[14:15]
	v_mov_b64_e32 v[48:49], v[14:15]
	v_mov_b64_e32 v[32:33], v[14:15]
	v_mov_b64_e32 v[62:63], v[12:13]
	v_mov_b64_e32 v[60:61], v[10:11]
	v_mov_b64_e32 v[58:59], v[8:9]
	v_mov_b64_e32 v[56:57], v[6:7]
	v_mov_b64_e32 v[54:55], v[4:5]
	v_mov_b64_e32 v[52:53], v[2:3]
	v_mov_b64_e32 v[50:51], v[0:1]
	v_mov_b64_e32 v[46:47], v[12:13]
	v_mov_b64_e32 v[44:45], v[10:11]
	v_mov_b64_e32 v[42:43], v[8:9]
	v_mov_b64_e32 v[40:41], v[6:7]
	v_mov_b64_e32 v[38:39], v[4:5]
	v_mov_b64_e32 v[36:37], v[2:3]
	v_mov_b64_e32 v[34:35], v[0:1]
	v_mov_b64_e32 v[30:31], v[12:13]
	v_mov_b64_e32 v[28:29], v[10:11]
	v_mov_b64_e32 v[26:27], v[8:9]
	v_mov_b64_e32 v[24:25], v[6:7]
	v_mov_b64_e32 v[22:23], v[4:5]
	v_mov_b64_e32 v[20:21], v[2:3]
	v_mov_b64_e32 v[18:19], v[0:1]
	v_mov_b64_e32 v[16:17], v[14:15]
	v_mov_b64_e32 v[14:15], v[12:13]
	v_mov_b64_e32 v[12:13], v[10:11]
	v_mov_b64_e32 v[10:11], v[8:9]
	v_mov_b64_e32 v[8:9], v[6:7]
	v_mov_b64_e32 v[6:7], v[4:5]
	v_mov_b64_e32 v[4:5], v[2:3]
	v_mov_b64_e32 v[2:3], v[0:1]
	s_waitcnt lgkmcnt(0)
	s_barrier
	v_readfirstlane_b32 s98, v247
	s_lshr_b32 s98, s98, 6
	s_lshl_b32 s98, s98, 10
	s_add_i32 s98, s98, 0x10000
	s_mov_b32 s99, 0x4000
	s_add_i32 m0, s98, 0x6000
	v_mov_b64_e32 v[66:67], v[210:211]
	global_load_lds_dwordx4 v[66:67], off
	v_add_co_u32_e32 v66, vcc, 0xffffff00, v66
	s_add_i32 m0, s98, 0x4000
	s_nop 0
	v_addc_co_u32_e32 v67, vcc, -1, v67, vcc
	global_load_lds_dwordx4 v[66:67], off
.LBB0_375:
	s_add_i32 s25, s26, 1
	s_cmp_lt_u32 s25, s20
	s_cselect_b64 s[14:15], -1, 0
	s_cmp_ge_u32 s25, s20
	s_cselect_b64 s[10:11], -1, 0
	s_add_i32 vcc_lo, s25, 1
	s_cmp_lt_u32 vcc_lo, s20
	s_cbranch_scc0 .LBB0_377
	s_add_i32 m0, s99, 0x4000
	s_cmp_eq_u32 m0, 0xc000
	s_cselect_b32 m0, 0, m0
	s_add_i32 m0, m0, s98
	s_add_i32 m0, m0, 0x2000
	v_lshl_add_u64 v[66:67], v[210:211], 0, s[36:37]
	global_load_lds_dwordx4 v[66:67], off
	v_add_co_u32_e32 v66, vcc, 0xffffff00, v66
	s_sub_i32 m0, m0, 0x2000
	s_nop 0
	v_addc_co_u32_e32 v67, vcc, -1, v67, vcc
	global_load_lds_dwordx4 v[66:67], off

.LBB0_381:
	s_andn2_b64 vcc, exec, s[14:15]
	s_cbranch_vccnz .LBB0_383
	s_add_i32 vcc_lo, s25, 1
	s_cmp_lt_u32 vcc_lo, s20
	s_cbranch_scc1 .Lsw_w2
	s_waitcnt vmcnt(0)
	s_branch .Lsw_wj

.Lsw_wj:
	v_and_b32_e32 v0, 63, v247
	s_add_i32 vcc_lo, s98, s99
	s_nop 0
	v_lshl_add_u32 v0, v0, 4, vcc_lo
	ds_read_b128 v[130:133], v0
	ds_read_b128 v[134:137], v0 offset:8192
	s_add_i32 s99, s99, 0x4000
	s_cmp_eq_u32 s99, 0xc000
	s_cselect_b32 s99, 0, s99
	s_sub_i32 s14, 0, s26
	s_waitcnt lgkmcnt(0)
	v_add_u32_e32 v0, s14, v208
	v_add_u32_e32 v66, s14, v225
	ds_write_b128 v0, v[130:133] offset:21504
	ds_write_b128 v66, v[134:137] offset:30720
